# 7 grid barriers (after P2,P8,P10,P12,P14,P15,P16) replaced by 32-WG XCD-group-local barriers without L2 writeback; runtime check that each blockIdx&7 group sits on one XCC, else full-barrier fallback
# speedup vs baseline: 1.0196x; 1.0152x over previous
_Z10fwd_kernel4Args:
	v_mov_b32_e32 v243, 0
	v_writelane_b32 v242, 0, 63
	s_load_dword s3, s[0:1], 0xd8
	s_load_dwordx4 s[76:79], s[0:1], 0xc0
	s_load_dwordx2 s[60:61], s[0:1], 0xd0
	v_and_b32_e32 v185, 0x3ff, v0
	s_add_u32 s6, s0, 0xd0
	v_readfirstlane_b32 s74, v185
	s_addc_u32 s7, s1, 0
	v_cmp_gt_u32_e32 vcc, 16, v185
	s_waitcnt lgkmcnt(0)
	v_writelane_b32 v242, s3, 0
	s_and_saveexec_b64 s[4:5], vcc
	v_lshl_add_u32 v1, v185, 2, 0
	v_add_u32_e32 v1, 0x21000, v1
	v_mov_b32_e32 v2, 0
	ds_write_b32 v1, v2
	s_or_b64 exec, exec, s[4:5]
	s_waitcnt lgkmcnt(0)
	s_barrier
	s_getreg_b32 s3, hwreg(HW_REG_XCC_ID, 0, 4)
	s_and_b32 s84, s3, 15
	v_cmp_eq_u32_e64 s[8:9], 0, v185
	s_mov_b64 s[4:5], exec
	s_nop 0
	v_writelane_b32 v242, s8, 1
	s_nop 1
	v_writelane_b32 v242, s9, 2
	s_and_b64 s[8:9], s[4:5], s[8:9]
	s_mov_b64 exec, s[8:9]
	s_cbranch_execz .LBB0_5
	s_mov_b64 s[8:9], exec
	v_mbcnt_lo_u32_b32 v1, s8, 0
	v_mbcnt_hi_u32_b32 v1, s9, v1
	v_cmp_eq_u32_e32 vcc, 0, v1
	s_and_b64 s[10:11], exec, vcc
	s_mov_b64 exec, s[10:11]
	s_cbranch_execz .LBB0_5
	s_and_b32 s3, s2, 7
	s_lshl_b32 s3, s3, 2
	s_add_u32 s3, s3, 0x3000
	v_mov_b32_e32 v1, s3
	s_lshl_b32 s3, 1, s84
	v_mov_b32_e32 v2, s3
	global_atomic_or v1, v2, s[76:77] offset:3072 sc1
	s_lshl_b32 s3, s84, 8
	s_bcnt1_i32_b64 s8, s[8:9]
	v_mov_b32_e32 v1, s3
	v_mov_b32_e32 v2, s8
	global_atomic_add v1, v2, s[76:77] offset:1024

.LBB0_100:
	s_or_b64 exec, exec, s[0:1]
	s_waitcnt lgkmcnt(0)
	s_barrier
	v_readlane_b32 s12, v242, 63
	s_add_u32 s12, s12, 1
	v_writelane_b32 v242, s12, 63
	v_and_b32_e32 v0, 7, v184
	v_lshlrev_b32_e32 v0, 2, v0
	v_add_u32_e32 v0, 0x3000, v0
	global_load_dword v0, v0, s[76:77] offset:3072 sc1
	s_mov_b32 s12, 1
	s_waitcnt vmcnt(0)
	v_readlane_b32 s13, v0, 0
	s_bcnt1_i32_b32 s13, s13
	s_cmp_eq_u32 s13, 1
	s_cselect_b32 s12, s12, 0
	v_readlane_b32 s13, v0, 1
	s_bcnt1_i32_b32 s13, s13
	s_cmp_eq_u32 s13, 1
	s_cselect_b32 s12, s12, 0
	v_readlane_b32 s13, v0, 2
	s_bcnt1_i32_b32 s13, s13
	s_cmp_eq_u32 s13, 1
	s_cselect_b32 s12, s12, 0
	v_readlane_b32 s13, v0, 3
	s_bcnt1_i32_b32 s13, s13
	s_cmp_eq_u32 s13, 1
	s_cselect_b32 s12, s12, 0
	v_readlane_b32 s13, v0, 4
	s_bcnt1_i32_b32 s13, s13
	s_cmp_eq_u32 s13, 1
	s_cselect_b32 s12, s12, 0
	v_readlane_b32 s13, v0, 5
	s_bcnt1_i32_b32 s13, s13
	s_cmp_eq_u32 s13, 1
	s_cselect_b32 s12, s12, 0
	v_readlane_b32 s13, v0, 6
	s_bcnt1_i32_b32 s13, s13
	s_cmp_eq_u32 s13, 1
	s_cselect_b32 s12, s12, 0
	v_readlane_b32 s13, v0, 7
	s_bcnt1_i32_b32 s13, s13
	s_cmp_eq_u32 s13, 1
	s_cselect_b32 s12, s12, 0
	s_cmp_eq_u32 s60, 0x100
	s_cselect_b32 s12, s12, 0
	v_writelane_b32 v243, s12, 0
